# q/k norm+rope loop: next item's x loads issued one iteration ahead + partial-rope cos/sin table computed once in phase 0 (same instruction sequence); on top of v9
# speedup vs baseline: 1.0034x; 1.0034x over previous
.LBB0_411:
	s_or_b64 exec, exec, s[0:1]
	s_mov_b64 s[0:1], 0x300000
	v_cmp_gt_u64_e32 vcc, s[0:1], v[134:135]
	s_and_saveexec_b64 s[2:3], vcc
	s_cbranch_execz .LBB0_416
	v_readlane_b32 s36, v247, 45
	v_ffbh_u32_e32 v0, 0
	v_readlane_b32 s38, v247, 47
	v_readlane_b32 s39, v247, 48
	v_readlane_b32 s40, v247, 49
	v_readlane_b32 s41, v247, 50
	v_min_u32_e32 v29, 32, v0
	s_mov_b64 s[4:5], 0
	v_mov_b32_e32 v1, 0
	v_mov_b32_e32 v24, s39
	v_mov_b32_e32 v25, s41
	v_mov_b32_e32 v26, s38
	v_mov_b32_e32 v27, s40
	v_mov_b32_e32 v28, 0x358637bd
	v_sub_u32_e32 v30, 32, v29
	v_mov_b64_e32 v[2:3], v[134:135]
	v_readlane_b32 s37, v247, 46
	v_readlane_b32 s42, v248, 18
	v_readlane_b32 s43, v248, 19
	v_readlane_b32 s44, v247, 53
	v_readlane_b32 s45, v247, 54
	v_readlane_b32 s46, v247, 55
	v_readlane_b32 s47, v247, 56
	v_readlane_b32 s48, v247, 57
	v_readlane_b32 s49, v247, 58
	v_readlane_b32 s50, v247, 59
	v_readlane_b32 s51, v247, 60
	s_mov_b32 s0, 0xaaaaaaab
	v_mul_hi_u32 v90, v2, s0
	v_lshrrev_b32_e32 v90, 6, v90
	s_movk_i32 s0, 0x60
	v_mul_lo_u32 v91, v90, s0
	v_sub_u32_e32 v91, v2, v91
	v_ashrrev_i32_e32 v92, 2, v91
	v_and_b32_e32 v93, 3, v91
	v_mul_hi_i32_i24_e32 v95, 0x1200, v90
	v_mul_i32_i24_e32 v94, 0x1200, v90
	v_lshlrev_b32_e32 v96, 6, v92
	v_lshl_add_u64 v[94:95], s[70:71], 0, v[94:95]
	v_ashrrev_i32_e32 v97, 31, v96
	v_lshl_add_u64 v[94:95], v[96:97], 1, v[94:95]
	v_lshlrev_b32_e32 v96, 5, v93
	v_mov_b32_e32 v97, 0
	v_lshl_add_u64 v[94:95], v[94:95], 0, v[96:97]
	global_load_dwordx4 v[80:83], v[94:95], off
	global_load_dwordx4 v[84:87], v[94:95], off offset:16
	s_waitcnt vmcnt(0)
	s_branch .LBB0_414

.LBB0_414:
	s_mov_b32 s0, 0xaaaaaaab
	v_mul_hi_u32 v0, v2, s0
	v_lshrrev_b32_e32 v13, 6, v0
	v_and_b32_e32 v61, 0x7ff, v13
	v_lshlrev_b32_e32 v61, 6, v61
	global_load_dwordx4 v[62:65], v61, s[42:43]
	global_load_dwordx4 v[66:69], v61, s[42:43] offset:16
	global_load_dwordx4 v[70:73], v61, s[42:43] offset:32
	global_load_dwordx4 v[74:77], v61, s[42:43] offset:48
	s_movk_i32 s0, 0x60
	v_mul_lo_u32 v0, v13, s0
	v_sub_u32_e32 v0, v2, v0
	v_ashrrev_i32_e32 v10, 2, v0
	v_mul_hi_i32_i24_e32 v5, 0x1200, v13
	v_mul_i32_i24_e32 v4, 0x1200, v13
	v_lshlrev_b32_e32 v6, 6, v10
	v_and_b32_e32 v31, 3, v0
	v_lshl_add_u64 v[4:5], s[70:71], 0, v[4:5]
	v_ashrrev_i32_e32 v7, 31, v6
	v_lshl_add_u64 v[4:5], v[6:7], 1, v[4:5]
	v_lshlrev_b32_e32 v0, 5, v31
	v_lshl_add_u64 v[4:5], v[4:5], 0, v[0:1]
	v_lshlrev_b32_e32 v0, 4, v10
	v_cmp_lt_i32_e32 vcc, 11, v10
	v_add_u32_e32 v12, 0xffffff40, v0
	s_mov_b32 s0, 0x800000
	v_cndmask_b32_e32 v0, v0, v12, vcc
	v_and_b32_e32 v18, 0xffffffc0, v0
	v_cndmask_b32_e32 v11, v24, v25, vcc
	v_cndmask_b32_e32 v10, v26, v27, vcc
	v_ashrrev_i32_e32 v19, 31, v18
	v_lshlrev_b32_e32 v0, 6, v31
	v_lshl_add_u64 v[10:11], v[18:19], 2, v[10:11]
	v_lshl_add_u64 v[10:11], v[10:11], 0, v[0:1]
	global_load_dwordx4 v[18:21], v[10:11], off
	global_load_dwordx4 v[32:35], v[10:11], off offset:16
	global_load_dwordx4 v[36:39], v[10:11], off offset:32
	global_load_dwordx4 v[40:43], v[10:11], off offset:48
	s_waitcnt vmcnt(10)
	v_mov_b32_e32 v6, v80
	v_mov_b32_e32 v7, v81
	v_mov_b32_e32 v8, v82
	v_mov_b32_e32 v9, v83
	v_mov_b32_e32 v14, v84
	v_mov_b32_e32 v15, v85
	v_mov_b32_e32 v16, v86
	v_mov_b32_e32 v17, v87
	v_add_u32_e32 v98, s26, v2
	v_min_u32_e32 v98, 0x2fffff, v98
	s_mov_b32 s0, 0xaaaaaaab
	v_mul_hi_u32 v90, v98, s0
	v_lshrrev_b32_e32 v90, 6, v90
	s_movk_i32 s0, 0x60
	v_mul_lo_u32 v91, v90, s0
	v_sub_u32_e32 v91, v98, v91
	v_ashrrev_i32_e32 v92, 2, v91
	v_and_b32_e32 v93, 3, v91
	v_mul_hi_i32_i24_e32 v95, 0x1200, v90
	v_mul_i32_i24_e32 v94, 0x1200, v90
	v_lshlrev_b32_e32 v96, 6, v92
	v_lshl_add_u64 v[94:95], s[70:71], 0, v[94:95]
	v_ashrrev_i32_e32 v97, 31, v96
	v_lshl_add_u64 v[94:95], v[96:97], 1, v[94:95]
	v_lshlrev_b32_e32 v96, 5, v93
	v_mov_b32_e32 v97, 0
	v_lshl_add_u64 v[94:95], v[94:95], 0, v[96:97]
	global_load_dwordx4 v[80:83], v[94:95], off
	global_load_dwordx4 v[84:87], v[94:95], off offset:16
	s_mov_b32 s0, 0x800000
	v_lshlrev_b32_e32 v10, 16, v6
	v_and_b32_e32 v11, 0xffff0000, v6
	v_lshlrev_b32_e32 v6, 16, v7
	v_and_b32_e32 v7, 0xffff0000, v7
	v_pk_mul_f32 v[48:49], v[10:11], v[10:11]
	v_pk_mul_f32 v[52:53], v[6:7], v[6:7]
	v_add_f32_e32 v0, v48, v49
	v_lshlrev_b32_e32 v22, 16, v8
	v_and_b32_e32 v23, 0xffff0000, v8
	v_add_f32_e32 v0, v0, v52
	v_pk_mul_f32 v[56:57], v[22:23], v[22:23]
	v_add_f32_e32 v0, v53, v0
	v_add_f32_e32 v0, v56, v0
	v_lshlrev_b32_e32 v12, 16, v9
	v_add_f32_e32 v0, v57, v0
	v_and_b32_e32 v60, 0xffff0000, v9
	v_lshlrev_b32_e32 v8, 16, v14
	v_and_b32_e32 v9, 0xffff0000, v14
	v_fmac_f32_e32 v0, v12, v12
	v_pk_mul_f32 v[50:51], v[8:9], v[8:9]
	v_fmac_f32_e32 v0, v60, v60
	v_lshlrev_b32_e32 v14, 16, v15
	v_and_b32_e32 v15, 0xffff0000, v15
	v_add_f32_e32 v0, v50, v0
	v_pk_mul_f32 v[54:55], v[14:15], v[14:15]
	v_add_f32_e32 v0, v51, v0
	v_lshlrev_b32_e32 v44, 16, v16
	v_and_b32_e32 v45, 0xffff0000, v16
	v_add_f32_e32 v0, v54, v0
	v_pk_mul_f32 v[58:59], v[44:45], v[44:45]
	v_add_f32_e32 v0, v55, v0
	v_lshlrev_b32_e32 v47, 16, v17
	v_and_b32_e32 v46, 0xffff0000, v17
	v_add_f32_e32 v0, v58, v0
	v_pk_mul_f32 v[16:17], v[46:47], v[46:47]
	v_add_f32_e32 v0, v59, v0
	v_add_f32_e32 v0, v17, v0
	v_add_f32_e32 v0, v16, v0
	s_nop 1
	v_add_f32_dpp v0, v0, v0 quad_perm:[1,0,3,2] row_mask:0xf bank_mask:0xf bound_ctrl:1
	s_nop 1
	v_add_f32_dpp v0, v0, v0 quad_perm:[2,3,0,1] row_mask:0xf bank_mask:0xf bound_ctrl:1
	v_fmamk_f32 v0, v0, 0x3c800000, v28
	v_mul_f32_e32 v16, 0x4b800000, v0
	v_cmp_gt_f32_e64 s[0:1], s0, v0
	s_nop 1
	v_cndmask_b32_e64 v0, v0, v16, s[0:1]
	v_rsq_f32_e32 v0, v0
	s_nop 0
	v_mul_f32_e32 v16, 0x45800000, v0
	v_cndmask_b32_e64 v0, v0, v16, s[0:1]
	v_mul_f32_e32 v16, 0x3e000000, v0
	v_cndmask_b32_e32 v0, v16, v0, vcc
	v_pk_mul_f32 v[10:11], v[0:1], v[10:11] op_sel_hi:[0,1]
	v_pk_mul_f32 v[16:17], v[0:1], v[22:23] op_sel_hi:[0,1]
	v_mul_f32_e32 v12, v0, v12
	v_mul_f32_e32 v48, v0, v47
	v_mov_b32_e32 v47, v60
	v_pk_mul_f32 v[6:7], v[0:1], v[6:7] op_sel_hi:[0,1]
	v_pk_mul_f32 v[8:9], v[0:1], v[8:9] op_sel_hi:[0,1]
	v_pk_mul_f32 v[14:15], v[0:1], v[14:15] op_sel_hi:[0,1]
	v_pk_mul_f32 v[44:45], v[0:1], v[44:45] op_sel_hi:[0,1]
	s_waitcnt vmcnt(5)
	v_pk_mul_f32 v[22:23], v[18:19], v[10:11]
	s_waitcnt vmcnt(4)
	v_pk_mul_f32 v[18:19], v[32:33], v[16:17]
	v_mul_f32_e32 v12, v34, v12
	v_pk_mul_f32 v[16:17], v[0:1], v[46:47] op_sel_hi:[0,1]
	s_waitcnt vmcnt(2)
	v_mov_b32_e32 v34, v43
	v_pk_mul_f32 v[20:21], v[20:21], v[6:7]
	v_pk_mul_f32 v[6:7], v[36:37], v[8:9]
	v_pk_mul_f32 v[8:9], v[38:39], v[14:15]
	v_pk_mul_f32 v[10:11], v[40:41], v[44:45]
	v_mul_f32_e32 v14, v42, v48
	v_pk_mul_f32 v[16:17], v[34:35], v[16:17]
	v_cmp_eq_u32_e32 vcc, 0, v31
	s_and_saveexec_b64 s[0:1], vcc
	s_cbranch_execz .LBB0_413
	v_pk_mul_f32 v[36:37], v[70:71], v[6:7]
	v_pk_fma_f32 v[36:37], v[62:63], v[22:23], v[36:37] neg_lo:[0,0,1] neg_hi:[0,0,1]
	v_pk_mul_f32 v[22:23], v[70:71], v[22:23]
	v_pk_mul_f32 v[34:35], v[72:73], v[8:9]
	v_pk_fma_f32 v[6:7], v[62:63], v[6:7], v[22:23]
	v_pk_fma_f32 v[34:35], v[64:65], v[20:21], v[34:35] neg_lo:[0,0,1] neg_hi:[0,0,1]
	v_pk_mul_f32 v[20:21], v[72:73], v[20:21]
	v_pk_mul_f32 v[32:33], v[74:75], v[10:11]
	v_pk_fma_f32 v[8:9], v[64:65], v[8:9], v[20:21]
	v_pk_fma_f32 v[32:33], v[66:67], v[18:19], v[32:33] neg_lo:[0,0,1] neg_hi:[0,0,1]
	v_pk_mul_f32 v[18:19], v[74:75], v[18:19]
	v_mov_b32_e32 v15, v16
	v_pk_fma_f32 v[10:11], v[66:67], v[10:11], v[18:19]
	v_mul_f32_e32 v22, v68, v14
	v_mul_f32_e32 v38, v76, v12
	v_mov_b32_e32 v13, v17
	v_mov_b32_e32 v78, v69
	v_mov_b32_e32 v79, v77
	v_pk_mul_f32 v[14:15], v[76:77], v[14:15]
	s_nop 0
	v_pk_fma_f32 v[12:13], v[68:69], v[12:13], v[14:15] neg_lo:[0,0,1] neg_hi:[0,0,1]
	v_pk_mul_f32 v[14:15], v[78:79], v[16:17]
	v_mov_b32_e32 v20, v34
	v_mov_b32_e32 v23, v14
	v_mov_b32_e32 v39, v15
	s_nop 0
	v_pk_add_f32 v[14:15], v[22:23], v[38:39]
	v_mov_b32_e32 v22, v36
	v_mov_b32_e32 v23, v37
	v_mov_b32_e32 v21, v35
	v_mov_b32_e32 v18, v32
	v_mov_b32_e32 v19, v33
	v_mov_b32_e32 v17, v13
	v_mov_b32_e32 v16, v15
	s_branch .LBB0_413
